# diff-latent attention loop hand-scheduled: all waves deferred-PV, PV(t-1) MFMAs interleaved with max/exp VALU of tile t
# speedup vs baseline: 1.0136x; 1.0136x over previous
.LBB0_925:
	s_bfe_u32 s8, s36, 0x10002
	s_lshl_b32 s1, s8, 12
	s_or_b32 s14, s1, 0x2000
	s_ashr_i32 s0, s36, 3
	s_and_b32 s9, s36, 3
	s_mul_i32 s1, s14, 0x2080
	s_add_u32 s1, s12, s1
	s_addc_u32 s3, s13, 0
	s_lshl_b32 s40, s9, 8
	s_add_u32 s2, s1, s40
	s_addc_u32 s3, s3, 0
	s_lshl_b32 s1, s9, 22
	s_add_u32 s1, s4, s1
	s_addc_u32 s7, s5, 0
	s_lshl_b32 s6, s14, 1
	s_add_u32 s6, s1, s6
	s_addc_u32 s7, s7, 0
	s_ashr_i32 s1, s0, 31
	s_lshl_b64 s[0:1], s[0:1], 7
	v_mov_b32_e32 v194, v206
	s_add_u32 s0, s0, s14
	s_addc_u32 s14, s1, 0
	v_readfirstlane_b32 s37, v194
	s_bfe_u32 s38, s37, 0x20006
	v_and_or_b32 v0, v194, 31, s0
	v_lshl_or_b32 v196, s38, 5, v0
	v_mov_b64_e32 v[0:1], s[12:13]
	s_ashr_i32 s39, s37, 8
	v_mad_u64_u32 v[162:163], s[0:1], v196, s79, v[0:1]
	v_mad_i32_i24 v163, s14, v211, v163
	s_lshl_b32 s0, s39, 6
	v_mov_b32_e32 v24, v206
	v_lshl_add_u64 v[0:1], v[162:163], 0, s[40:41]
	s_ashr_i32 s1, s0, 31
	v_lshl_add_u64 v[0:1], s[0:1], 1, v[0:1]
	v_lshrrev_b32_e32 v2, 1, v24
	v_and_b32_e32 v164, 16, v2
	v_mov_b32_e32 v165, v193
	v_lshl_add_u64 v[0:1], v[0:1], 0, v[164:165]
	v_lshlrev_b32_e32 v25, 3, v24
	global_load_dwordx4 v[140:143], v[0:1], off offset:2048
	global_load_dwordx4 v[136:139], v[0:1], off offset:2080
	global_load_dwordx4 v[132:135], v[0:1], off offset:2112
	global_load_dwordx4 v[128:131], v[0:1], off offset:2144
	v_and_b32_e32 v0, 56, v25
	v_lshlrev_b32_e32 v192, 1, v0
	v_lshl_add_u64 v[0:1], s[6:7], 0, v[192:193]
	s_mov_b64 s[6:7], 0x22000000
	v_lshl_add_u64 v[14:15], v[0:1], 0, s[6:7]
	v_ashrrev_i32_e32 v0, 31, v24
	v_lshrrev_b32_e32 v0, 28, v0
	v_add_u32_e32 v0, v24, v0
	v_add_u32_e32 v16, 0x200, v24
	v_ashrrev_i32_e32 v197, 4, v0
	v_and_b32_e32 v0, -16, v0
	v_ashrrev_i32_e32 v12, 31, v16
	v_sub_u32_e32 v26, v24, v0
	v_lshrrev_b32_e32 v12, 28, v12
	v_lshlrev_b32_e32 v168, 3, v26
	v_add_u32_e32 v12, v16, v12
	v_mov_b64_e32 v[10:11], s[2:3]
	v_ashrrev_i32_e32 v169, 31, v168
	v_ashrrev_i32_e32 v170, 3, v24
	v_ashrrev_i32_e32 v198, 4, v12
	v_and_b32_e32 v12, -16, v12
	v_mad_i64_i32 v[2:3], s[6:7], v197, s79, v[10:11]
	v_lshlrev_b64 v[0:1], 1, v[168:169]
	v_ashrrev_i32_e32 v171, 31, v170
	v_sub_u32_e32 v27, v16, v12
	v_lshl_add_u64 v[2:3], v[2:3], 0, v[0:1]
	v_lshlrev_b64 v[6:7], 15, v[170:171]
	v_lshlrev_b32_e32 v172, 3, v27
	global_load_dwordx4 v[2:5], v[2:3], off offset:3072
	v_lshl_add_u64 v[18:19], v[14:15], 0, v[6:7]
	v_ashrrev_i32_e32 v173, 31, v172
	v_ashrrev_i32_e32 v174, 3, v16
	global_load_dwordx4 v[6:9], v[18:19], off
	v_mad_i64_i32 v[10:11], s[6:7], v198, s79, v[10:11]
	v_lshlrev_b64 v[20:21], 1, v[172:173]
	v_ashrrev_i32_e32 v175, 31, v174
	v_lshl_add_u64 v[10:11], v[10:11], 0, v[20:21]
	v_lshlrev_b64 v[16:17], 15, v[174:175]
	global_load_dwordx4 v[10:13], v[10:11], off offset:3072
	v_lshl_add_u64 v[22:23], v[14:15], 0, v[16:17]
	global_load_dwordx4 v[14:17], v[22:23], off
	v_mov_b32_e32 v195, s14
	v_readfirstlane_b32 s14, v24
	v_and_b32_e32 v32, 31, v24
	v_lshlrev_b32_e32 v24, 4, v24
	s_movk_i32 s6, 0x110
	v_and_b32_e32 v24, 0x60, v24
	v_and_b32_e32 v25, 8, v25
	v_mul_lo_u32 v202, v197, s6
	v_add3_u32 v199, 0, v24, v25
	v_add_u32_e32 v24, 0, v202
	v_lshlrev_b32_e32 v203, 4, v26
	v_mul_lo_u32 v201, v170, s80
	s_cmpk_gt_i32 s14, 0xff
	v_add_u32_e32 v200, v24, v203
	v_add_u32_e32 v24, v199, v201
	s_mov_b64 s[0:1], -1
	s_cmpk_lt_i32 s14, 0x100
	v_mul_lo_u32 v220, v198, s6
	s_mov_b64 s[14:15], 0
	v_lshlrev_b32_e32 v221, 4, v27
	v_mul_lo_u32 v219, v174, s80
	s_add_u32 s6, s2, 0x82c00
	v_add_u32_e32 v25, v199, v219
	s_addc_u32 s7, s3, 0
	s_add_u32 s2, s2, 0x104c00
	s_addc_u32 s3, s3, 0
	v_mul_u32_u24_e32 v26, 0x110, v32
	s_mov_b32 s54, s41
	s_mov_b32 s55, s41
	s_mov_b32 s40, s41
	s_mov_b32 s42, s41
	s_mov_b32 s43, s41
	s_mov_b32 s44, s41
	s_mov_b32 s45, s41
	s_mov_b32 s46, s41
	s_mov_b32 s47, s41
	s_mov_b32 s48, s41
	s_mov_b32 s49, s41
	s_mov_b32 s50, s41
	s_mov_b32 s51, s41
	s_mov_b32 s52, s41
	s_mov_b32 s53, s41
	v_mov_b64_e32 v[62:63], s[54:55]
	v_add_u32_e32 v33, 0, v164
	v_mov_b64_e32 v[48:49], s[40:41]
	v_mul_u32_u24_e32 v165, 0x90, v32
	v_mov_b64_e32 v[60:61], s[52:53]
	v_mov_b64_e32 v[58:59], s[50:51]
	v_mov_b64_e32 v[56:57], s[48:49]
	v_mov_b64_e32 v[54:55], s[46:47]
	v_mov_b64_e32 v[52:53], s[44:45]
	v_mov_b64_e32 v[50:51], s[42:43]
	v_add_u32_e32 v175, v33, v165
	s_and_b64 vcc, exec, s[0:1]
	s_waitcnt vmcnt(0) lgkmcnt(0)
	ds_write_b128 v200, v[2:5]
	v_add_u32_e32 v2, 0x8800, v24
	ds_write2_b64 v2, v[6:7], v[8:9] offset1:2
	v_add_u32_e32 v2, 0, v220
	v_add_u32_e32 v205, v2, v221
	v_add_u32_e32 v2, 0x8800, v25
	ds_write_b128 v205, v[10:13]
	v_mov_b64_e32 v[10:11], s[6:7]
	ds_write2_b64 v2, v[14:15], v[16:17] offset1:2
	v_mad_i64_i32 v[2:3], s[6:7], v197, s79, v[10:11]
	v_lshl_add_u64 v[2:3], v[2:3], 0, v[0:1]
	v_mad_i64_i32 v[10:11], s[6:7], v198, s79, v[10:11]
	global_load_dwordx4 v[2:5], v[2:3], off
	s_nop 0
	global_load_dwordx4 v[6:9], v[18:19], off offset:128
	v_lshl_add_u64 v[10:11], v[10:11], 0, v[20:21]
	global_load_dwordx4 v[10:13], v[10:11], off
	s_nop 0
	global_load_dwordx4 v[14:17], v[22:23], off offset:128
	s_waitcnt lgkmcnt(0)
	s_barrier
	s_waitcnt vmcnt(0)
	ds_write_b128 v200, v[2:5] offset:17408
	v_add_u32_e32 v2, 0xd000, v24
	ds_write2_b64 v2, v[6:7], v[8:9] offset1:2
	ds_write_b128 v205, v[10:13] offset:17408
	v_add_u32_e32 v2, 0xd000, v25
	ds_write2_b64 v2, v[14:15], v[16:17] offset1:2
	v_mov_b64_e32 v[2:3], s[2:3]
	v_mad_i64_i32 v[4:5], s[2:3], v197, s79, v[2:3]
	v_lshl_add_u64 v[0:1], v[4:5], 0, v[0:1]
	global_load_dwordx4 v[156:159], v[0:1], off
	global_load_dwordx4 v[148:151], v[18:19], off offset:256
	v_mad_i64_i32 v[0:1], s[2:3], v198, s79, v[2:3]
	v_lshl_add_u64 v[0:1], v[0:1], 0, v[20:21]
	global_load_dwordx4 v[152:155], v[0:1], off
	global_load_dwordx4 v[144:147], v[22:23], off offset:256
	s_lshl_b32 s2, s39, 7
	s_add_i32 s2, s2, 0
	v_add3_u32 v171, s2, v26, v164
	ds_read_b128 v[16:19], v171 offset:8704
	ds_read_b128 v[0:3], v171
	ds_read_b128 v[34:37], v171 offset:32
	s_waitcnt lgkmcnt(0)
	v_mfma_f32_32x32x16_bf16 v[0:15], v[0:3], v[140:143], 0
	ds_read_b128 v[38:41], v171 offset:8736
	v_mfma_f32_32x32x16_bf16 v[16:31], v[16:19], v[140:143], 0
	v_mfma_f32_32x32x16_bf16 v[0:15], v[34:37], v[136:139], v[0:15]
	s_waitcnt lgkmcnt(0)
	v_mfma_f32_32x32x16_bf16 v[16:31], v[38:41], v[136:139], v[16:31]
	ds_read_b128 v[34:37], v171 offset:8768
	ds_read_b128 v[38:41], v171 offset:64
	s_waitcnt lgkmcnt(0)
	v_mfma_f32_32x32x16_bf16 v[0:15], v[38:41], v[132:135], v[0:15]
	v_mfma_f32_32x32x16_bf16 v[16:31], v[34:37], v[132:135], v[16:31]
	ds_read_b128 v[34:37], v171 offset:8800
	ds_read_b128 v[38:41], v171 offset:96
	s_waitcnt lgkmcnt(0)
	v_mfma_f32_32x32x16_bf16 v[0:15], v[38:41], v[128:131], v[0:15]
	v_mfma_f32_32x32x16_bf16 v[16:31], v[34:37], v[128:131], v[16:31]
	s_nop 10
	v_max_f32_e32 v34, v1, v1
	v_max_f32_e32 v35, v0, v0
	v_max_f32_e32 v34, v35, v34
	v_max3_f32 v35, v2, v3, v17
	v_max3_f32 v34, v34, v16, v18
	v_max3_f32 v34, v34, v19, v4
	v_max3_f32 v35, v35, v6, v7
	v_max3_f32 v34, v34, v5, v20
	v_max3_f32 v35, v35, v22, v23
	v_max3_f32 v34, v34, v21, v8
	v_max3_f32 v35, v35, v10, v11
	v_max3_f32 v34, v34, v9, v24
	v_max3_f32 v35, v35, v26, v27
	v_max3_f32 v34, v34, v25, v12
	v_max3_f32 v35, v35, v14, v15
	v_max3_f32 v34, v34, v13, v28
	v_max3_f32 v35, v35, v30, v31
	v_max3_f32 v34, v34, v29, v35
	v_mov_b32_e32 v35, v34
	s_nop 1
	v_permlane32_swap_b32_e32 v34, v35
	v_max_f32_e32 v35, v35, v35
	v_max_f32_e32 v34, v34, v34
	v_max_f32_e32 v112, v34, v35
	v_sub_f32_e32 v0, v0, v112
	v_sub_f32_e32 v16, v16, v112
	v_sub_f32_e32 v1, v1, v112
	v_sub_f32_e32 v17, v17, v112
	v_sub_f32_e32 v2, v2, v112
	v_sub_f32_e32 v18, v18, v112
	v_sub_f32_e32 v3, v3, v112
	v_sub_f32_e32 v19, v19, v112
	v_sub_f32_e32 v4, v4, v112
	v_sub_f32_e32 v20, v20, v112
	v_sub_f32_e32 v5, v5, v112
	v_sub_f32_e32 v21, v21, v112
	v_sub_f32_e32 v6, v6, v112
	v_sub_f32_e32 v22, v22, v112
	v_sub_f32_e32 v7, v7, v112
	v_sub_f32_e32 v23, v23, v112
	v_sub_f32_e32 v8, v8, v112
	v_sub_f32_e32 v24, v24, v112
	v_sub_f32_e32 v9, v9, v112
	v_sub_f32_e32 v25, v25, v112
	v_sub_f32_e32 v10, v10, v112
	v_sub_f32_e32 v26, v26, v112
	v_sub_f32_e32 v11, v11, v112
	v_sub_f32_e32 v27, v27, v112
	v_sub_f32_e32 v12, v12, v112
	v_sub_f32_e32 v28, v28, v112
	v_sub_f32_e32 v13, v13, v112
	v_sub_f32_e32 v29, v29, v112
	v_sub_f32_e32 v14, v14, v112
	v_sub_f32_e32 v30, v30, v112
	v_sub_f32_e32 v15, v15, v112
	v_sub_f32_e32 v31, v31, v112
	v_exp_f32_e32 v64, v0
	v_exp_f32_e32 v65, v1
	v_exp_f32_e32 v66, v16
	v_exp_f32_e32 v67, v17
	v_exp_f32_e32 v68, v2
	v_exp_f32_e32 v69, v3
	v_exp_f32_e32 v70, v18
	v_exp_f32_e32 v71, v19
	v_exp_f32_e32 v72, v4
	v_exp_f32_e32 v73, v5
	v_exp_f32_e32 v74, v20
	v_exp_f32_e32 v75, v21
	v_exp_f32_e32 v76, v6
	v_exp_f32_e32 v77, v7
	v_exp_f32_e32 v78, v22
	v_exp_f32_e32 v79, v23
	v_exp_f32_e32 v80, v8
	v_exp_f32_e32 v81, v9
	v_exp_f32_e32 v82, v24
	v_exp_f32_e32 v83, v25
	v_exp_f32_e32 v84, v10
	v_exp_f32_e32 v85, v11
	v_exp_f32_e32 v86, v26
	v_exp_f32_e32 v87, v27
	v_exp_f32_e32 v88, v12
	v_exp_f32_e32 v89, v13
	v_exp_f32_e32 v90, v28
	v_exp_f32_e32 v91, v29
	v_exp_f32_e32 v92, v14
	v_exp_f32_e32 v93, v15
	v_exp_f32_e32 v94, v30
	v_exp_f32_e32 v95, v31
	v_mov_b64_e32 v[32:33], v[48:49]
	v_mov_b64_e32 v[16:17], v[48:49]
	v_mov_b64_e32 v[0:1], v[48:49]
	v_cvt_pk_bf16_f32 v104, v64, v65
	v_cvt_pk_bf16_f32 v105, v68, v69
	v_cvt_pk_bf16_f32 v106, v72, v73
	v_cvt_pk_bf16_f32 v107, v76, v77
	v_cvt_pk_bf16_f32 v96, v66, v67
	v_cvt_pk_bf16_f32 v97, v70, v71
	v_cvt_pk_bf16_f32 v98, v74, v75
	v_cvt_pk_bf16_f32 v99, v78, v79
	v_cvt_pk_bf16_f32 v108, v80, v81
	v_cvt_pk_bf16_f32 v109, v84, v85
	v_cvt_pk_bf16_f32 v110, v88, v89
	v_cvt_pk_bf16_f32 v111, v92, v93
	v_cvt_pk_bf16_f32 v100, v82, v83
	v_cvt_pk_bf16_f32 v101, v86, v87
	v_cvt_pk_bf16_f32 v102, v90, v91
	v_cvt_pk_bf16_f32 v103, v94, v95
	v_mov_b64_e32 v[34:35], v[50:51]
	v_mov_b64_e32 v[36:37], v[52:53]
	v_mov_b64_e32 v[38:39], v[54:55]
	v_mov_b64_e32 v[40:41], v[56:57]
	v_mov_b64_e32 v[42:43], v[58:59]
	v_mov_b64_e32 v[44:45], v[60:61]
	v_mov_b64_e32 v[46:47], v[62:63]
	v_mov_b64_e32 v[18:19], v[50:51]
	v_mov_b64_e32 v[20:21], v[52:53]
	v_mov_b64_e32 v[22:23], v[54:55]
	v_mov_b64_e32 v[24:25], v[56:57]
	v_mov_b64_e32 v[26:27], v[58:59]
	v_mov_b64_e32 v[28:29], v[60:61]
	v_mov_b64_e32 v[30:31], v[62:63]
	v_mov_b64_e32 v[2:3], v[50:51]
	v_mov_b64_e32 v[4:5], v[52:53]
	v_mov_b64_e32 v[6:7], v[54:55]
	v_mov_b64_e32 v[8:9], v[56:57]
	v_mov_b64_e32 v[10:11], v[58:59]
	v_mov_b64_e32 v[12:13], v[60:61]
	v_mov_b64_e32 v[14:15], v[62:63]
	s_cbranch_vccnz .LBB0_927
	ds_read_b128 v[240:243], v175 offset:34816
	ds_read_b128 v[244:247], v175 offset:34848
	ds_read_b128 v[248:251], v175 offset:34880
	ds_read_b128 v[252:255], v175 offset:34912
	s_waitcnt lgkmcnt(3)
	v_mfma_f32_32x32x16_bf16 v[48:63], v[240:243], v[104:107], 0
	ds_read_b128 v[240:243], v175 offset:39424
	s_waitcnt lgkmcnt(3)
	v_mfma_f32_32x32x16_bf16 v[48:63], v[244:247], v[108:111], v[48:63]
	ds_read_b128 v[244:247], v175 offset:39456
	s_waitcnt lgkmcnt(3)
	v_mfma_f32_32x32x16_bf16 v[48:63], v[248:251], v[96:99], v[48:63]
	ds_read_b128 v[248:251], v175 offset:39488
	s_waitcnt lgkmcnt(3)
	v_mfma_f32_32x32x16_bf16 v[48:63], v[252:255], v[100:103], v[48:63]
	ds_read_b128 v[252:255], v175 offset:39520
	s_waitcnt lgkmcnt(3)
	v_mfma_f32_32x32x16_bf16 v[32:47], v[240:243], v[104:107], 0
	ds_read_b128 v[240:243], v175 offset:44032
	s_waitcnt lgkmcnt(3)
	v_mfma_f32_32x32x16_bf16 v[32:47], v[244:247], v[108:111], v[32:47]
	ds_read_b128 v[244:247], v175 offset:44064
	s_waitcnt lgkmcnt(3)
	v_mfma_f32_32x32x16_bf16 v[32:47], v[248:251], v[96:99], v[32:47]
	ds_read_b128 v[248:251], v175 offset:44096
	s_waitcnt lgkmcnt(3)
	v_mfma_f32_32x32x16_bf16 v[32:47], v[252:255], v[100:103], v[32:47]
	ds_read_b128 v[252:255], v175 offset:44128
	s_waitcnt lgkmcnt(3)
	v_mfma_f32_32x32x16_bf16 v[16:31], v[240:243], v[104:107], 0
	ds_read_b128 v[240:243], v175 offset:48640
	s_waitcnt lgkmcnt(3)
	v_mfma_f32_32x32x16_bf16 v[16:31], v[244:247], v[108:111], v[16:31]
	ds_read_b128 v[244:247], v175 offset:48672
	s_waitcnt lgkmcnt(3)
	v_mfma_f32_32x32x16_bf16 v[16:31], v[248:251], v[96:99], v[16:31]
	ds_read_b128 v[248:251], v175 offset:48704
	s_waitcnt lgkmcnt(3)
	v_mfma_f32_32x32x16_bf16 v[16:31], v[252:255], v[100:103], v[16:31]
	ds_read_b128 v[252:255], v175 offset:48736
	s_waitcnt lgkmcnt(3)
	v_mfma_f32_32x32x16_bf16 v[0:15], v[240:243], v[104:107], 0
	s_waitcnt lgkmcnt(2)
	v_mfma_f32_32x32x16_bf16 v[0:15], v[244:247], v[108:111], v[0:15]
	s_waitcnt lgkmcnt(1)
	v_mfma_f32_32x32x16_bf16 v[0:15], v[248:251], v[96:99], v[0:15]
	s_waitcnt lgkmcnt(0)
	v_mfma_f32_32x32x16_bf16 v[0:15], v[252:255], v[100:103], v[0:15]

.LBB0_931:
	v_lshl_add_u64 v[64:65], s[22:23], 0, v[192:193]
	v_mad_i64_i32 v[66:67], s[22:23], s20, v197, 0
	v_lshl_add_u64 v[66:67], v[66:67], 1, s[6:7]
	v_lshl_add_u64 v[66:67], v[168:169], 1, v[66:67]
	global_load_dwordx4 v[156:159], v[66:67], off
	v_mad_i64_i32 v[66:67], s[22:23], s8, v170, 0
	v_lshl_add_u64 v[66:67], v[66:67], 1, v[64:65]
	global_load_dwordx4 v[148:151], v[66:67], off
	v_mad_i64_i32 v[66:67], s[20:21], s20, v198, 0
	v_lshl_add_u64 v[66:67], v[66:67], 1, s[6:7]
	v_lshl_add_u64 v[66:67], v[172:173], 1, v[66:67]
	global_load_dwordx4 v[152:155], v[66:67], off
	v_mad_i64_i32 v[66:67], s[6:7], s8, v174, 0
	v_lshl_add_u64 v[64:65], v[66:67], 1, v[64:65]
	global_load_dwordx4 v[144:147], v[64:65], off
	s_mov_b64 s[8:9], 0
	s_mul_i32 s6, s47, 0x4800
	v_add_u32_e32 v69, s6, v175
	s_mulk_i32 s48, 0x4400
	v_add_u32_e32 v68, s48, v171
	s_mov_b32 s6, 0x40c00000
	ds_read_b128 v[72:75], v68
	ds_read_b128 v[76:79], v68 offset:8704
	ds_read_b128 v[222:225], v68 offset:32
	s_waitcnt lgkmcnt(2)
	v_mfma_f32_32x32x16_bf16 v[112:127], v[72:75], v[140:143], v[80:95]
	ds_read_b128 v[72:75], v68 offset:8736
	s_waitcnt lgkmcnt(2)
	v_mfma_f32_32x32x16_bf16 v[240:255], v[76:79], v[140:143], v[80:95]
	ds_read_b128 v[76:79], v68 offset:64
	s_waitcnt lgkmcnt(2)
	v_mfma_f32_32x32x16_bf16 v[112:127], v[222:225], v[136:139], v[112:127]
	ds_read_b128 v[222:225], v68 offset:8768
	s_waitcnt lgkmcnt(2)
	v_mfma_f32_32x32x16_bf16 v[240:255], v[72:75], v[136:139], v[240:255]
	ds_read_b128 v[72:75], v68 offset:96
	s_waitcnt lgkmcnt(2)
	v_mfma_f32_32x32x16_bf16 v[112:127], v[76:79], v[132:135], v[112:127]
	ds_read_b128 v[76:79], v68 offset:8800
	s_waitcnt lgkmcnt(2)
	v_mfma_f32_32x32x16_bf16 v[240:255], v[222:225], v[132:135], v[240:255]
	ds_read_b128 v[222:225], v69 offset:34816
	s_waitcnt lgkmcnt(2)
	v_mfma_f32_32x32x16_bf16 v[112:127], v[72:75], v[128:131], v[112:127]
	ds_read_b128 v[72:75], v69 offset:34848
	s_waitcnt lgkmcnt(2)
	v_mfma_f32_32x32x16_bf16 v[240:255], v[76:79], v[128:131], v[240:255]
	ds_read_b128 v[76:79], v69 offset:34880
	s_waitcnt lgkmcnt(2)
	v_mfma_f32_32x32x16_bf16 v[48:63], v[222:225], v[104:107], v[48:63]
	ds_read_b128 v[222:225], v69 offset:34912
	s_waitcnt lgkmcnt(2)
	v_mfma_f32_32x32x16_bf16 v[48:63], v[72:75], v[108:111], v[48:63]
	ds_read_b128 v[72:75], v69 offset:39424
	s_waitcnt lgkmcnt(2)
	v_mfma_f32_32x32x16_bf16 v[48:63], v[76:79], v[96:99], v[48:63]
	ds_read_b128 v[76:79], v69 offset:39456
	s_waitcnt lgkmcnt(2)
	v_mfma_f32_32x32x16_bf16 v[48:63], v[222:225], v[100:103], v[48:63]
	ds_read_b128 v[222:225], v69 offset:39488
	v_max_f32_e32 v70, v113, v113
	v_max_f32_e32 v71, v112, v112
	v_max_f32_e32 v70, v71, v70
	v_max3_f32 v64, v114, v115, v241
	v_max3_f32 v65, v70, v240, v242
	s_waitcnt lgkmcnt(2)
	v_mfma_f32_32x32x16_bf16 v[32:47], v[72:75], v[104:107], v[32:47]
	ds_read_b128 v[72:75], v69 offset:39520
	v_max3_f32 v65, v65, v243, v116
	v_max3_f32 v64, v64, v118, v119
	v_max3_f32 v65, v65, v117, v244
	v_max3_f32 v64, v64, v246, v247
	v_max3_f32 v65, v65, v245, v120
	s_waitcnt lgkmcnt(2)
	v_mfma_f32_32x32x16_bf16 v[32:47], v[76:79], v[108:111], v[32:47]
	ds_read_b128 v[76:79], v69 offset:44032
	v_max3_f32 v64, v64, v122, v123
	v_max3_f32 v65, v65, v121, v248
	v_max3_f32 v64, v64, v250, v251
	v_max3_f32 v65, v65, v249, v124
	v_max3_f32 v64, v64, v126, v127
	s_waitcnt lgkmcnt(2)
	v_mfma_f32_32x32x16_bf16 v[32:47], v[222:225], v[96:99], v[32:47]
	ds_read_b128 v[222:225], v69 offset:44064
	v_max3_f32 v65, v65, v125, v252
	v_max3_f32 v64, v64, v254, v255
	v_max3_f32 v64, v65, v253, v64
	v_mov_b32_e32 v65, v64
	s_waitcnt lgkmcnt(2)
	v_mfma_f32_32x32x16_bf16 v[32:47], v[72:75], v[100:103], v[32:47]
	ds_read_b128 v[72:75], v69 offset:44096
	v_permlane32_swap_b32_e32 v64, v65
	v_max_f32_e32 v65, v65, v65
	v_max_f32_e32 v64, v64, v64
	v_max_f32_e32 v64, v64, v65
	v_cmp_lt_f32_e32 vcc, s6, v64
	s_cbranch_vccnz .Ldl_rare
	s_waitcnt lgkmcnt(2)
	v_mfma_f32_32x32x16_bf16 v[16:31], v[76:79], v[104:107], v[16:31]
	ds_read_b128 v[76:79], v69 offset:44128
	v_exp_f32_e32 v112, v112
	v_exp_f32_e32 v113, v113
	v_exp_f32_e32 v176, v240
	s_waitcnt lgkmcnt(2)
	v_mfma_f32_32x32x16_bf16 v[16:31], v[222:225], v[108:111], v[16:31]
	ds_read_b128 v[222:225], v69 offset:48640
	v_exp_f32_e32 v177, v241
	v_exp_f32_e32 v114, v114
	v_exp_f32_e32 v115, v115
	s_waitcnt lgkmcnt(2)
	v_mfma_f32_32x32x16_bf16 v[16:31], v[72:75], v[96:99], v[16:31]
	ds_read_b128 v[72:75], v69 offset:48672
	v_exp_f32_e32 v178, v242
	v_exp_f32_e32 v179, v243
	v_exp_f32_e32 v116, v116
	s_waitcnt lgkmcnt(2)
	v_mfma_f32_32x32x16_bf16 v[16:31], v[76:79], v[100:103], v[16:31]
	ds_read_b128 v[76:79], v69 offset:48704
	v_exp_f32_e32 v117, v117
	v_exp_f32_e32 v180, v244
	v_exp_f32_e32 v181, v245
	s_waitcnt lgkmcnt(2)
	v_mfma_f32_32x32x16_bf16 v[0:15], v[222:225], v[104:107], v[0:15]
	ds_read_b128 v[222:225], v69 offset:48736
	v_exp_f32_e32 v118, v118
	v_exp_f32_e32 v119, v119
	v_exp_f32_e32 v182, v246
	s_waitcnt lgkmcnt(2)
	v_mfma_f32_32x32x16_bf16 v[0:15], v[72:75], v[108:111], v[0:15]
	v_exp_f32_e32 v183, v247
	v_exp_f32_e32 v120, v120
	v_exp_f32_e32 v121, v121
	s_waitcnt lgkmcnt(1)
	v_mfma_f32_32x32x16_bf16 v[0:15], v[76:79], v[96:99], v[0:15]
	v_exp_f32_e32 v184, v248
	v_exp_f32_e32 v185, v249
	v_exp_f32_e32 v122, v122
	s_waitcnt lgkmcnt(0)
	v_mfma_f32_32x32x16_bf16 v[0:15], v[222:225], v[100:103], v[0:15]
	v_exp_f32_e32 v123, v123
	v_exp_f32_e32 v186, v250
	v_exp_f32_e32 v187, v251
	v_exp_f32_e32 v124, v124
	v_exp_f32_e32 v125, v125
	v_exp_f32_e32 v188, v252
	v_exp_f32_e32 v189, v253
	v_exp_f32_e32 v126, v126
	v_exp_f32_e32 v127, v127
	v_exp_f32_e32 v190, v254
	v_exp_f32_e32 v191, v255
.Ldl_join:
	v_cvt_pk_bf16_f32 v104, v112, v113
	v_cvt_pk_bf16_f32 v105, v114, v115
	v_cvt_pk_bf16_f32 v106, v116, v117
	v_cvt_pk_bf16_f32 v107, v118, v119
	v_cvt_pk_bf16_f32 v96, v176, v177
	v_cvt_pk_bf16_f32 v97, v178, v179
	v_cvt_pk_bf16_f32 v98, v180, v181
	v_cvt_pk_bf16_f32 v99, v182, v183
	v_cvt_pk_bf16_f32 v108, v120, v121
	v_cvt_pk_bf16_f32 v109, v122, v123
	v_cvt_pk_bf16_f32 v110, v124, v125
	v_cvt_pk_bf16_f32 v111, v126, v127
	v_cvt_pk_bf16_f32 v100, v184, v185
	v_cvt_pk_bf16_f32 v101, v186, v187
	v_cvt_pk_bf16_f32 v102, v188, v189
	v_cvt_pk_bf16_f32 v103, v190, v191
	s_mov_b64 s[6:7], -1
	v_pk_add_f32 v[112:113], v[112:113], 0 op_sel_hi:[1,0]
	v_pk_add_f32 v[176:177], v[176:177], 0 op_sel_hi:[1,0]
	v_pk_add_f32 v[112:113], v[114:115], v[112:113]
	v_pk_add_f32 v[114:115], v[178:179], v[176:177]
	v_pk_add_f32 v[112:113], v[116:117], v[112:113]
	v_pk_add_f32 v[114:115], v[180:181], v[114:115]
	v_pk_add_f32 v[112:113], v[118:119], v[112:113]
	v_pk_add_f32 v[114:115], v[182:183], v[114:115]
	v_pk_add_f32 v[112:113], v[120:121], v[112:113]
	v_pk_add_f32 v[114:115], v[184:185], v[114:115]
	s_add_i32 s46, s46, 1
	s_add_i32 s20, s45, 1
	v_pk_add_f32 v[112:113], v[122:123], v[112:113]
	v_pk_add_f32 v[114:115], v[186:187], v[114:115]
	s_cmp_lg_u32 s20, 3
	v_pk_add_f32 v[112:113], v[124:125], v[112:113]
	v_pk_add_f32 v[114:115], v[188:189], v[114:115]
	s_cselect_b32 s20, s20, 0
	s_add_u32 s16, s16, 0x80
	v_pk_add_f32 v[112:113], v[126:127], v[112:113]
	v_pk_add_f32 v[114:115], v[190:191], v[114:115]
	s_addc_u32 s17, s17, 0
	v_pk_add_f32 v[112:113], v[114:115], v[112:113]
	s_add_u32 s18, s18, 0x82000
	s_waitcnt lgkmcnt(0)
	s_barrier
	v_add_f32_e32 v112, v112, v113
	s_addc_u32 s19, s19, 0
	v_add_f32_e32 v166, v166, v112
	s_cmpk_eq_i32 s46, 0x46
	s_cbranch_scc1 .LBB0_940
	s_mov_b32 s47, s3
	s_mov_b32 s3, s45
	s_mov_b32 s45, s20
	s_branch .LBB0_928
.Ldl_rare:
	s_waitcnt lgkmcnt(2)
	v_mfma_f32_32x32x16_bf16 v[16:31], v[76:79], v[104:107], v[16:31]
	ds_read_b128 v[76:79], v69 offset:44128
	s_waitcnt lgkmcnt(2)
	v_mfma_f32_32x32x16_bf16 v[16:31], v[222:225], v[108:111], v[16:31]
	ds_read_b128 v[222:225], v69 offset:48640
	s_waitcnt lgkmcnt(2)
	v_mfma_f32_32x32x16_bf16 v[16:31], v[72:75], v[96:99], v[16:31]
	ds_read_b128 v[72:75], v69 offset:48672
	s_waitcnt lgkmcnt(2)
	v_mfma_f32_32x32x16_bf16 v[16:31], v[76:79], v[100:103], v[16:31]
	ds_read_b128 v[76:79], v69 offset:48704
	s_waitcnt lgkmcnt(2)
	v_mfma_f32_32x32x16_bf16 v[0:15], v[222:225], v[104:107], v[0:15]
	ds_read_b128 v[222:225], v69 offset:48736
	s_waitcnt lgkmcnt(2)
	v_mfma_f32_32x32x16_bf16 v[0:15], v[72:75], v[108:111], v[0:15]
	s_waitcnt lgkmcnt(1)
	v_mfma_f32_32x32x16_bf16 v[0:15], v[76:79], v[96:99], v[0:15]
	s_waitcnt lgkmcnt(0)
	v_mfma_f32_32x32x16_bf16 v[0:15], v[222:225], v[100:103], v[0:15]
	v_max_f32_e32 v64, v64, v64
	v_max_f32_e32 v64, 0, v64
	v_exp_f32_e64 v66, -v64
	v_mov_b32_e32 v67, v64
	v_pk_add_f32 v[112:113], v[112:113], v[64:65] op_sel_hi:[1,0] neg_lo:[0,1] neg_hi:[0,1]
	v_pk_add_f32 v[240:241], v[240:241], v[64:65] op_sel_hi:[1,0] neg_lo:[0,1] neg_hi:[0,1]
	v_pk_add_f32 v[114:115], v[114:115], v[64:65] op_sel_hi:[1,0] neg_lo:[0,1] neg_hi:[0,1]
	v_pk_add_f32 v[242:243], v[242:243], v[64:65] op_sel_hi:[1,0] neg_lo:[0,1] neg_hi:[0,1]
	v_pk_add_f32 v[116:117], v[116:117], v[64:65] op_sel_hi:[1,0] neg_lo:[0,1] neg_hi:[0,1]
	v_pk_add_f32 v[244:245], v[244:245], v[64:65] op_sel_hi:[1,0] neg_lo:[0,1] neg_hi:[0,1]
	v_pk_add_f32 v[118:119], v[118:119], v[64:65] op_sel_hi:[1,0] neg_lo:[0,1] neg_hi:[0,1]
	v_pk_add_f32 v[246:247], v[246:247], v[64:65] op_sel_hi:[1,0] neg_lo:[0,1] neg_hi:[0,1]
	v_pk_add_f32 v[120:121], v[120:121], v[64:65] op_sel_hi:[1,0] neg_lo:[0,1] neg_hi:[0,1]
	v_pk_add_f32 v[248:249], v[248:249], v[64:65] op_sel_hi:[1,0] neg_lo:[0,1] neg_hi:[0,1]
	v_pk_add_f32 v[122:123], v[122:123], v[64:65] op_sel_hi:[1,0] neg_lo:[0,1] neg_hi:[0,1]
	v_pk_add_f32 v[250:251], v[250:251], v[64:65] op_sel_hi:[1,0] neg_lo:[0,1] neg_hi:[0,1]
	v_pk_add_f32 v[124:125], v[124:125], v[64:65] op_sel_hi:[1,0] neg_lo:[0,1] neg_hi:[0,1]
	v_pk_add_f32 v[252:253], v[252:253], v[64:65] op_sel_hi:[1,0] neg_lo:[0,1] neg_hi:[0,1]
	v_pk_add_f32 v[126:127], v[126:127], v[64:65] op_sel_hi:[1,0] neg_lo:[0,1] neg_hi:[0,1]
	v_pk_add_f32 v[254:255], v[254:255], v[64:65] op_sel_hi:[1,0] neg_lo:[0,1] neg_hi:[0,1]
	v_pk_add_f32 v[64:65], v[166:167], v[66:67]
	v_pk_mul_f32 v[166:167], v[166:167], v[66:67]
	v_xor_b32_e32 v64, 0x80000000, v65
	v_mov_b32_e32 v167, v65
	v_pk_mul_f32 v[62:63], v[62:63], v[66:67] op_sel_hi:[1,0]
	v_pk_mul_f32 v[60:61], v[60:61], v[66:67] op_sel_hi:[1,0]
	v_pk_mul_f32 v[58:59], v[58:59], v[66:67] op_sel_hi:[1,0]
	v_pk_mul_f32 v[56:57], v[56:57], v[66:67] op_sel_hi:[1,0]
	v_pk_mul_f32 v[54:55], v[54:55], v[66:67] op_sel_hi:[1,0]
	v_pk_mul_f32 v[52:53], v[52:53], v[66:67] op_sel_hi:[1,0]
	v_pk_mul_f32 v[50:51], v[50:51], v[66:67] op_sel_hi:[1,0]
	v_pk_mul_f32 v[48:49], v[48:49], v[66:67] op_sel_hi:[1,0]
	v_pk_mul_f32 v[46:47], v[46:47], v[66:67] op_sel_hi:[1,0]
	v_pk_mul_f32 v[44:45], v[44:45], v[66:67] op_sel_hi:[1,0]
	v_pk_mul_f32 v[42:43], v[42:43], v[66:67] op_sel_hi:[1,0]
	v_pk_mul_f32 v[40:41], v[40:41], v[66:67] op_sel_hi:[1,0]
	v_pk_mul_f32 v[38:39], v[38:39], v[66:67] op_sel_hi:[1,0]
	v_pk_mul_f32 v[36:37], v[36:37], v[66:67] op_sel_hi:[1,0]
	v_pk_mul_f32 v[34:35], v[34:35], v[66:67] op_sel_hi:[1,0]
	v_pk_mul_f32 v[32:33], v[32:33], v[66:67] op_sel_hi:[1,0]
	v_pk_mul_f32 v[30:31], v[30:31], v[66:67] op_sel_hi:[1,0]
	v_pk_mul_f32 v[28:29], v[28:29], v[66:67] op_sel_hi:[1,0]
	v_pk_mul_f32 v[26:27], v[26:27], v[66:67] op_sel_hi:[1,0]
	v_pk_mul_f32 v[24:25], v[24:25], v[66:67] op_sel_hi:[1,0]
	v_pk_mul_f32 v[22:23], v[22:23], v[66:67] op_sel_hi:[1,0]
	v_pk_mul_f32 v[20:21], v[20:21], v[66:67] op_sel_hi:[1,0]
	v_pk_mul_f32 v[18:19], v[18:19], v[66:67] op_sel_hi:[1,0]
	v_pk_mul_f32 v[16:17], v[16:17], v[66:67] op_sel_hi:[1,0]
	v_pk_mul_f32 v[14:15], v[14:15], v[66:67] op_sel_hi:[1,0]
	v_pk_mul_f32 v[12:13], v[12:13], v[66:67] op_sel_hi:[1,0]
	v_pk_mul_f32 v[10:11], v[10:11], v[66:67] op_sel_hi:[1,0]
	v_pk_mul_f32 v[8:9], v[8:9], v[66:67] op_sel_hi:[1,0]
	v_pk_mul_f32 v[6:7], v[6:7], v[66:67] op_sel_hi:[1,0]
	v_pk_mul_f32 v[4:5], v[4:5], v[66:67] op_sel_hi:[1,0]
	v_pk_mul_f32 v[2:3], v[2:3], v[66:67] op_sel_hi:[1,0]
	v_pk_mul_f32 v[0:1], v[0:1], v[66:67] op_sel_hi:[1,0]
	v_mov_b32_e32 v80, v64
	v_mov_b32_e32 v81, v64
	v_mov_b32_e32 v82, v64
	v_mov_b32_e32 v83, v64
	v_mov_b32_e32 v84, v64
	v_mov_b32_e32 v85, v64
	v_mov_b32_e32 v86, v64
	v_mov_b32_e32 v87, v64
	v_mov_b32_e32 v88, v64
	v_mov_b32_e32 v89, v64
	v_mov_b32_e32 v90, v64
	v_mov_b32_e32 v91, v64
	v_mov_b32_e32 v92, v64
	v_mov_b32_e32 v93, v64
	v_mov_b32_e32 v94, v64
	v_mov_b32_e32 v95, v64
	v_exp_f32_e32 v112, v112
	v_exp_f32_e32 v113, v113
	v_exp_f32_e32 v176, v240
	v_exp_f32_e32 v177, v241
	v_exp_f32_e32 v114, v114
	v_exp_f32_e32 v115, v115
	v_exp_f32_e32 v178, v242
	v_exp_f32_e32 v179, v243
	v_exp_f32_e32 v116, v116
	v_exp_f32_e32 v117, v117
	v_exp_f32_e32 v180, v244
	v_exp_f32_e32 v181, v245
	v_exp_f32_e32 v118, v118
	v_exp_f32_e32 v119, v119
	v_exp_f32_e32 v182, v246
	v_exp_f32_e32 v183, v247
	v_exp_f32_e32 v120, v120
	v_exp_f32_e32 v121, v121
	v_exp_f32_e32 v184, v248
	v_exp_f32_e32 v185, v249
	v_exp_f32_e32 v122, v122
	v_exp_f32_e32 v123, v123
	v_exp_f32_e32 v186, v250
	v_exp_f32_e32 v187, v251
	v_exp_f32_e32 v124, v124
	v_exp_f32_e32 v125, v125
	v_exp_f32_e32 v188, v252
	v_exp_f32_e32 v189, v253
	v_exp_f32_e32 v126, v126
	v_exp_f32_e32 v127, v127
	v_exp_f32_e32 v190, v254
	v_exp_f32_e32 v191, v255
	s_branch .Ldl_join
.LBB0_940:
	v_mov_b64_e32 v[64:65], v[80:81]
	v_mov_b64_e32 v[66:67], v[82:83]
	v_mov_b64_e32 v[68:69], v[84:85]
	v_mov_b64_e32 v[70:71], v[86:87]
	v_mov_b64_e32 v[72:73], v[88:89]
	v_mov_b64_e32 v[74:75], v[90:91]
	v_mov_b64_e32 v[76:77], v[92:93]
	v_mov_b64_e32 v[78:79], v[94:95]
	v_add_u32_e32 v80, 0x8800, v199
	v_add_u32_e32 v81, v80, v201
	v_add_u32_e32 v80, v80, v219
	v_add_u32_e32 v81, 0x9000, v81
	v_add_u32_e32 v80, 0x9000, v80
	s_and_b64 vcc, exec, s[8:9]
	s_waitcnt vmcnt(0)
	ds_write_b128 v200, v[156:159] offset:17408
	ds_write2_b64 v81, v[148:149], v[150:151] offset1:2
	ds_write_b128 v205, v[152:155] offset:17408
	ds_write2_b64 v80, v[144:145], v[146:147] offset1:2
	s_cbranch_vccnz .LBB0_942
	ds_read_b128 v[240:243], v175 offset:34816
	ds_read_b128 v[244:247], v175 offset:34848
	ds_read_b128 v[248:251], v175 offset:34880
	ds_read_b128 v[252:255], v175 offset:34912
	s_waitcnt lgkmcnt(3)
	v_mfma_f32_32x32x16_bf16 v[48:63], v[240:243], v[104:107], v[48:63]
	ds_read_b128 v[240:243], v175 offset:39424
	s_waitcnt lgkmcnt(3)
	v_mfma_f32_32x32x16_bf16 v[48:63], v[244:247], v[108:111], v[48:63]
	ds_read_b128 v[244:247], v175 offset:39456
	s_waitcnt lgkmcnt(3)
	v_mfma_f32_32x32x16_bf16 v[48:63], v[248:251], v[96:99], v[48:63]
	ds_read_b128 v[248:251], v175 offset:39488
	s_waitcnt lgkmcnt(3)
	v_mfma_f32_32x32x16_bf16 v[48:63], v[252:255], v[100:103], v[48:63]
	ds_read_b128 v[252:255], v175 offset:39520
	s_waitcnt lgkmcnt(3)
	v_mfma_f32_32x32x16_bf16 v[32:47], v[240:243], v[104:107], v[32:47]
	ds_read_b128 v[240:243], v175 offset:44032
	s_waitcnt lgkmcnt(3)
	v_mfma_f32_32x32x16_bf16 v[32:47], v[244:247], v[108:111], v[32:47]
	ds_read_b128 v[244:247], v175 offset:44064
	s_waitcnt lgkmcnt(3)
	v_mfma_f32_32x32x16_bf16 v[32:47], v[248:251], v[96:99], v[32:47]
	ds_read_b128 v[248:251], v175 offset:44096
	s_waitcnt lgkmcnt(3)
	v_mfma_f32_32x32x16_bf16 v[32:47], v[252:255], v[100:103], v[32:47]
	ds_read_b128 v[252:255], v175 offset:44128
	s_waitcnt lgkmcnt(3)
	v_mfma_f32_32x32x16_bf16 v[16:31], v[240:243], v[104:107], v[16:31]
	ds_read_b128 v[240:243], v175 offset:48640
	s_waitcnt lgkmcnt(3)
	v_mfma_f32_32x32x16_bf16 v[16:31], v[244:247], v[108:111], v[16:31]
	ds_read_b128 v[244:247], v175 offset:48672
	s_waitcnt lgkmcnt(3)
	v_mfma_f32_32x32x16_bf16 v[16:31], v[248:251], v[96:99], v[16:31]
	ds_read_b128 v[248:251], v175 offset:48704
	s_waitcnt lgkmcnt(3)
	v_mfma_f32_32x32x16_bf16 v[16:31], v[252:255], v[100:103], v[16:31]
	ds_read_b128 v[252:255], v175 offset:48736
	s_waitcnt lgkmcnt(3)
	v_mfma_f32_32x32x16_bf16 v[0:15], v[240:243], v[104:107], v[0:15]
	s_waitcnt lgkmcnt(2)
	v_mfma_f32_32x32x16_bf16 v[0:15], v[244:247], v[108:111], v[0:15]
	s_waitcnt lgkmcnt(1)
	v_mfma_f32_32x32x16_bf16 v[0:15], v[248:251], v[96:99], v[0:15]
	s_waitcnt lgkmcnt(0)
	v_mfma_f32_32x32x16_bf16 v[0:15], v[252:255], v[100:103], v[0:15]
